# v7 + ssd chunk loop rewritten like rwkv (transposed xdt/a LDS layout -> one b128 read per 4 steps, mid-loop staging, lean barrier)
# speedup vs baseline: 1.0196x; 1.0196x over previous
; __device__ __forceinline__ float bf2f(bf16_t v) { return __uint_as_float(((unsigned)v) << 16); }
; __device__ __forceinline__ float lo2f(unsigned w) { return __uint_as_float(w << 16); }
; __device__ __forceinline__ float hi2f(unsigned w) { return __uint_as_float(w & 0xffff0000u); }
; __device__ __forceinline__ void ssd_scan_unit(CP p, int l, int u, char* smem) {
;     ...
;   auto gload = [&](int c) {
;     const int rb = rowof(b, c * 16);
; #pragma unroll
;     for (int x = 0; x < 2; ++x) {
;       const int e = tid + x * 256, tok = e >> 5, rem = e & 31, which = rem >> 4, part = rem & 15;
;       st[x] = *reinterpret_cast<const uint4*>(SS + (size_t)(rb + tok) * 768 + 256 + which * 256 + g * 128 + part * 8);
;     }
;     {
;       const int tok = tid >> 4, pp = tid & 15;
;       stxr = SS[(size_t)(rb + tok) * 768 + h * 64 + q * 16 + pp];
;       stdt = SD[(size_t)(rb + tok) * 4 + h];
;     }
;   };
;   auto lwrite = [&](int bi) {
; #pragma unroll
;     for (int x = 0; x < 2; ++x) {
;       const int e = tid + x * 256, tok = e >> 5, rem = e & 31, which = rem >> 4, part = rem & 15;
;       float* d = buf + bi * 16 * SST + tok * SST + which * 128 + part * 8;
;       *reinterpret_cast<float4*>(d) = make_float4(lo2f(st[x].x), hi2f(st[x].x), lo2f(st[x].y), hi2f(st[x].y));
;       *reinterpret_cast<float4*>(d + 4) = make_float4(lo2f(st[x].z), hi2f(st[x].z), lo2f(st[x].w), hi2f(st[x].w));
;     }
;     {
;       const int tok = tid >> 4, pp = tid & 15;
;       float* d = buf + bi * 16 * SST + tok * SST;
;       const float stx = bf2f(stxr);
;       d[256 + pp] = stx * stdt;
;       d[272 + pp] = stx;
;       if (pp == 0) d[288] = __expf(stdt * Ah);
;     }
;   };
;   half_barrier(smem);
;   gload(0);
;   lwrite(0);
;   half_barrier(smem);
.LBB0_534:
	s_or_b64 exec, exec, s[2:3]
	s_lshr_b32 s2, s11, 2
	s_lshl_b32 s2, s2, 6
	s_and_b32 s10, s57, 0x70
	s_and_b32 s4, s2, 0x80
	s_lshl_b32 s2, s11, 4
	s_bitset1_b32 s10, 14
	s_and_b32 s2, s2, 48
	s_lshl_b32 s3, s28, 7
	s_add_u32 s3, s44, s3
	s_addc_u32 s5, s45, 0
	s_lshl_b32 s29, s2, 1
	s_add_u32 s72, s3, s29
	s_waitcnt vmcnt(1)
	v_mul_f32_e32 v0, 0x3fb8aa3b, v0
	v_ashrrev_i32_e32 v47, 5, v12
	v_lshlrev_b32_e32 v2, 4, v12
	s_addc_u32 s73, s5, 0
	s_lshl_b32 s2, s28, 2
	v_exp_f32_e32 v46, v0
	v_add_u32_e32 v0, s10, v47
	v_mov_b64_e32 v[4:5], s[44:45]
	v_and_b32_e32 v2, 0x100, v2
	s_add_u32 s40, s88, s2
	v_mad_i64_i32 v[0:1], s[2:3], v0, s0, v[4:5]
	v_lshlrev_b32_e32 v148, 1, v2
	v_lshlrev_b32_e32 v13, 3, v12
	v_add_u32_e32 v6, 0x100, v12
	s_addc_u32 s41, s94, 0
	v_lshl_add_u64 v[0:1], v[0:1], 0, v[148:149]
	s_lshl_b32 s80, s4, 1
	v_and_b32_e32 v18, 0x78, v13
	v_ashrrev_i32_e32 v48, 5, v6
	v_lshl_add_u64 v[0:1], v[0:1], 0, s[80:81]
	v_lshlrev_b32_e32 v8, 1, v18
	v_mov_b32_e32 v9, v149
	v_add_u32_e32 v6, s10, v48
	v_lshl_add_u64 v[0:1], v[0:1], 0, v[8:9]
	v_mad_i64_i32 v[4:5], s[2:3], v6, s0, v[4:5]
	global_load_dwordx4 v[0:3], v[0:1], off offset:512
	v_lshl_add_u64 v[4:5], v[4:5], 0, v[148:149]
	v_lshl_add_u64 v[4:5], v[4:5], 0, s[80:81]
	v_ashrrev_i32_e32 v45, 4, v12
	v_lshl_add_u64 v[4:5], v[4:5], 0, v[8:9]
	v_and_b32_e32 v44, 15, v12
	global_load_dwordx4 v[4:7], v[4:5], off offset:512
	v_add_u32_e32 v14, s10, v45
	v_mov_b64_e32 v[10:11], s[72:73]
	v_mad_i64_i32 v[16:17], s[2:3], v14, s0, v[10:11]
	v_lshlrev_b32_e32 v10, 1, v44
	v_mov_b32_e32 v11, v149
	v_ashrrev_i32_e32 v15, 31, v14
	v_lshl_add_u64 v[16:17], v[16:17], 0, v[10:11]
	global_load_ushort v49, v[16:17], off
	v_lshl_add_u64 v[14:15], v[14:15], 4, s[40:41]
	global_load_dword v54, v[14:15], off
	s_movk_i32 s1, 0x128
	v_mul_lo_u32 v50, v47, s1
	v_and_b32_e32 v11, 0x80, v13
	v_lshl_add_u32 v9, v50, 2, s63
	v_lshlrev_b32_e32 v51, 2, v11
	v_lshlrev_b32_e32 v52, 2, v18
	v_add3_u32 v9, v9, v51, v52
	v_mul_lo_u32 v53, v48, s1
	v_mul_lo_u32 v55, v45, s1
	v_cmp_eq_u32_e64 s[38:39], 0, v44
	s_waitcnt vmcnt(3)
	v_lshlrev_b32_e32 v14, 16, v0
	v_and_b32_e32 v15, 0xffff0000, v0
	v_lshlrev_b32_e32 v16, 16, v1
	v_and_b32_e32 v17, 0xffff0000, v1
	ds_write_b128 v9, v[14:17]
	v_lshlrev_b32_e32 v14, 16, v2
	v_and_b32_e32 v15, 0xffff0000, v2
	v_lshlrev_b32_e32 v16, 16, v3
	v_and_b32_e32 v17, 0xffff0000, v3
	ds_write_b128 v9, v[14:17] offset:16
	v_lshl_add_u32 v9, v53, 2, s63
	v_add3_u32 v9, v9, v51, v52
	s_waitcnt vmcnt(2)
	v_lshlrev_b32_e32 v14, 16, v4
	v_and_b32_e32 v15, 0xffff0000, v4
	v_lshlrev_b32_e32 v16, 16, v5
	v_and_b32_e32 v17, 0xffff0000, v5
	ds_write_b128 v9, v[14:17]
	v_lshlrev_b32_e32 v14, 16, v6
	v_and_b32_e32 v15, 0xffff0000, v6
	v_lshlrev_b32_e32 v16, 16, v7
	v_and_b32_e32 v17, 0xffff0000, v7
	ds_write_b128 v9, v[14:17] offset:16
	v_lshl_add_u32 v9, v55, 2, s63
	s_waitcnt vmcnt(1)
	v_lshlrev_b32_e32 v11, 16, v49
	v_mul_u32_u24_e32 v83, 0x4a0, v44
	v_lshl_add_u32 v83, v45, 2, v83
	v_add_u32_e32 v83, 0x400, v83
	s_waitcnt vmcnt(0)
	v_mul_f32_e32 v13, v54, v11
	v_add_u32_e32 v14, s63, v83
	ds_write2_b32 v14, v13, v11 offset1:16
	s_and_saveexec_b64 s[2:3], s[38:39]
	s_cbranch_execz .LBB0_536
	v_mul_f32_e32 v11, v54, v46
	v_mul_f32_e32 v11, 0xbfb8aa3b, v11
	v_exp_f32_e32 v11, v11
	v_lshl_add_u32 v9, v45, 2, s63
	ds_write_b32 v9, v11 offset:37888

; __device__ __forceinline__ void ssd_scan_unit(CP p, int l, int u, char* smem) {
;     ...
;   half_barrier(smem);
;   gload(0);
;   lwrite(0);
;   half_barrier(smem);
;   constexpr int NCH = T / 16;
;   for (int c = 0; c < NCH; ++c) {
;     if (c + 1 < NCH) gload(c + 1);
;     const float* cb = buf + (c & 1) * 16 * SST;
;     float ykeep = 0.f;
;     float4 B0 = *reinterpret_cast<const float4*>(cb + j * 4), B1 = *reinterpret_cast<const float4*>(cb + 64 + j * 4);
;     float4 C0 = *reinterpret_cast<const float4*>(cb + 128 + j * 4), C1 = *reinterpret_cast<const float4*>(cb + 192 + j * 4);
;     float xdt = cb[256 + prow], xr = cb[272 + prow], a = cb[288];
; #pragma unroll 2
;     for (int s = 0; s < 16; ++s) {
;       const float* sb = cb + (s + 1) * SST;
;       const float4 B0n = *reinterpret_cast<const float4*>(sb + j * 4), B1n = *reinterpret_cast<const float4*>(sb + 64 + j * 4);
;       const float4 C0n = *reinterpret_cast<const float4*>(sb + 128 + j * 4), C1n = *reinterpret_cast<const float4*>(sb + 192 + j * 4);
;       const float xdtn = sb[256 + prow], xrn = sb[272 + prow], an = sb[288];
;       __builtin_amdgcn_sched_barrier(0);
;       hs[0] = fmaf(a, hs[0], xdt * B0.x); hs[1] = fmaf(a, hs[1], xdt * B0.y); hs[2] = fmaf(a, hs[2], xdt * B0.z); hs[3] = fmaf(a, hs[3], xdt * B0.w);
;       hs[4] = fmaf(a, hs[4], xdt * B1.x); hs[5] = fmaf(a, hs[5], xdt * B1.y); hs[6] = fmaf(a, hs[6], xdt * B1.z); hs[7] = fmaf(a, hs[7], xdt * B1.w);
;       float y = hs[0] * C0.x + hs[1] * C0.y + hs[2] * C0.z + hs[3] * C0.w + hs[4] * C1.x + hs[5] * C1.y + hs[6] * C1.z + hs[7] * C1.w;
;       y = allreduce16(y);
;       y = fmaf(Dh, xr, y);
;       if (j == s) ykeep = y;
;       B0 = B0n; B1 = B1n; C0 = C0n; C1 = C1n; xdt = xdtn; xr = xrn; a = an;
;     }
.LBB0_542:
	s_or_b64 exec, exec, s[2:3]
	s_lshl_b32 s3, s11, 7
	s_lshl_b32 s2, s28, 6
	s_and_b32 s11, s3, 0x3800
	s_add_i32 s11, s11, -16
	s_lshl_b32 s2, s2, 1
	v_readlane_b32 s4, v254, 7
	v_mov_b32_e32 v11, v149
	v_readlane_b32 s5, v254, 8
	s_add_u32 s2, s4, s2
	v_lshrrev_b32_e32 v9, 4, v12
	v_lshl_add_u64 v[26:27], s[72:73], 0, v[10:11]
	v_lshl_add_u64 v[10:11], s[44:45], 0, v[148:149]
	s_addc_u32 s3, s5, 0
	v_bfe_u32 v12, v12, 4, 2
	v_bfi_b32 v24, -4, v45, v9
	v_lshl_add_u64 v[10:11], v[10:11], 0, s[80:81]
	v_mov_b32_e32 v9, v149
	s_add_u32 s2, s2, s29
	v_lshl_add_u64 v[30:31], v[10:11], 0, v[8:9]
	v_lshlrev_b32_e32 v8, 2, v45
	v_lshlrev_b32_e32 v9, 2, v12
	s_addc_u32 s3, s3, 0
	v_ashrrev_i32_e32 v25, 31, v24
	v_and_or_b32 v8, v8, -16, v9
	v_mov_b32_e32 v32, 0
	v_lshlrev_b32_e32 v56, 2, v44
	v_lshl_add_u64 v[28:29], v[24:25], 1, s[2:3]
	v_add_u32_e32 v25, 0x8a0, v8
	v_lshlrev_b32_e32 v57, 4, v44
	s_mov_b32 s4, 0
	s_mov_b64 s[72:73], 0
	v_mov_b32_e32 v33, v32
	v_mov_b32_e32 v38, v32
	v_mov_b32_e32 v39, v32
	v_mov_b32_e32 v36, v32
	v_mov_b32_e32 v37, v32
	v_mov_b32_e32 v34, v32
	v_mov_b32_e32 v35, v32
	v_mov_b32_e32 v193, 0x20000
	v_lshl_add_u32 v193, v213, 2, v193
	v_mov_b32_e32 v195, 1
	ds_read_b32 v194, v193 offset:8
	v_mul_u32_u24_e32 v82, 0x4a0, v24
	v_lshl_add_u32 v81, v44, 2, v82
	s_add_i32 s5, s11, 16
	v_add_u32_e32 v8, s5, v45
	v_add_u32_e32 v0, s5, v47
	v_add_u32_e32 v4, s5, v48
	v_ashrrev_i32_e32 v9, 31, v8
	v_mad_i64_i32 v[0:1], s[12:13], v0, s0, v[30:31]
	v_mad_i64_i32 v[4:5], s[12:13], v4, s0, v[30:31]
	v_mad_i64_i32 v[10:11], s[12:13], v8, s0, v[26:27]
	v_lshl_add_u64 v[8:9], v[8:9], 4, s[40:41]
	global_load_dwordx4 v[0:3], v[0:1], off offset:512
	global_load_dwordx4 v[4:7], v[4:5], off offset:512
	global_load_ushort v49, v[10:11], off
	global_load_dword v54, v[8:9], off
	s_waitcnt lgkmcnt(0)
	v_and_b32_e32 v194, -4, v194
.Lsd_head:
	s_add_i32 s28, s4, 1
	s_bitcmp1_b32 s4, 0
	s_cselect_b32 s12, 0x4a00, 0
	s_cselect_b32 s13, 0x40, 0
	s_add_i32 s12, s63, s12
	s_add_i32 s13, s63, s13
	v_lshl_add_u32 v84, v56, 2, s12
	v_add_u32_e32 v85, s12, v82
	v_mov_b32_e32 v86, s13
	v_add_u32_e32 v87, s12, v81
	ds_read_b128 v[106:109], v85 offset:1024
	ds_read_b128 v[134:137], v86 offset:37888
	ds_read_b128 v[90:93], v84 offset:0
	ds_read_b128 v[94:97], v84 offset:256
	ds_read_b128 v[98:101], v84 offset:512
	ds_read_b128 v[102:105], v84 offset:768
	ds_read_b128 v[112:115], v84 offset:1184
	ds_read_b128 v[116:119], v84 offset:1440
	ds_read_b128 v[120:123], v84 offset:1696
	ds_read_b128 v[124:127], v84 offset:1952
	ds_read_b32 v186, v87 offset:1088
	s_waitcnt lgkmcnt(7)
	v_pk_mul_f32 v[176:177], v[90:91], v[106:107] op_sel_hi:[1,0]
	v_pk_mul_f32 v[178:179], v[92:93], v[106:107] op_sel_hi:[1,0]
	v_pk_mul_f32 v[180:181], v[94:95], v[106:107] op_sel_hi:[1,0]
	v_pk_mul_f32 v[182:183], v[96:97], v[106:107] op_sel_hi:[1,0]
	ds_read_b128 v[90:93], v84 offset:2368
	ds_read_b128 v[94:97], v84 offset:2624
	s_waitcnt lgkmcnt(5)
	v_pk_fma_f32 v[32:33], v[134:135], v[32:33], v[176:177] op_sel_hi:[0,1,1]
	v_pk_fma_f32 v[38:39], v[134:135], v[38:39], v[178:179] op_sel_hi:[0,1,1]
	v_pk_fma_f32 v[36:37], v[134:135], v[36:37], v[180:181] op_sel_hi:[0,1,1]
	v_pk_fma_f32 v[34:35], v[134:135], v[34:35], v[182:183] op_sel_hi:[0,1,1]
	v_pk_mul_f32 v[184:185], v[32:33], v[98:99]
	v_pk_mul_f32 v[176:177], v[112:113], v[106:107] op_sel:[0,1]
	v_pk_fma_f32 v[184:185], v[38:39], v[100:101], v[184:185]
	v_pk_mul_f32 v[178:179], v[114:115], v[106:107] op_sel:[0,1]
	v_pk_fma_f32 v[184:185], v[36:37], v[102:103], v[184:185]
	v_pk_mul_f32 v[180:181], v[116:117], v[106:107] op_sel:[0,1]
	v_pk_fma_f32 v[184:185], v[34:35], v[104:105], v[184:185]
	v_pk_mul_f32 v[182:183], v[118:119], v[106:107] op_sel:[0,1]
	v_add_f32_e32 v160, v184, v185
	ds_read_b128 v[112:115], v84 offset:3552
	ds_read_b128 v[116:119], v84 offset:3808
	ds_read_b128 v[98:101], v84 offset:2880
	ds_read_b128 v[102:105], v84 offset:3136
	ds_read_b128 v[128:131], v85 offset:1040
	ds_read_b128 v[138:141], v86 offset:37904
	s_waitcnt lgkmcnt(6)
	v_pk_fma_f32 v[32:33], v[134:135], v[32:33], v[176:177] op_sel:[1,0,0]
	v_pk_fma_f32 v[38:39], v[134:135], v[38:39], v[178:179] op_sel:[1,0,0]
	v_pk_fma_f32 v[36:37], v[134:135], v[36:37], v[180:181] op_sel:[1,0,0]
	v_pk_fma_f32 v[34:35], v[134:135], v[34:35], v[182:183] op_sel:[1,0,0]
	v_pk_mul_f32 v[184:185], v[32:33], v[120:121]
	v_pk_mul_f32 v[176:177], v[90:91], v[108:109] op_sel_hi:[1,0]
	v_pk_fma_f32 v[184:185], v[38:39], v[122:123], v[184:185]
	v_pk_mul_f32 v[178:179], v[92:93], v[108:109] op_sel_hi:[1,0]
	v_pk_fma_f32 v[184:185], v[36:37], v[124:125], v[184:185]
	v_pk_mul_f32 v[180:181], v[94:95], v[108:109] op_sel_hi:[1,0]
	v_pk_fma_f32 v[184:185], v[34:35], v[126:127], v[184:185]
	v_pk_mul_f32 v[182:183], v[96:97], v[108:109] op_sel_hi:[1,0]
	v_add_f32_e32 v161, v184, v185
	ds_read_b128 v[90:93], v84 offset:4736
	ds_read_b128 v[94:97], v84 offset:4992
	ds_read_b128 v[120:123], v84 offset:4064
	ds_read_b128 v[124:127], v84 offset:4320
	s_waitcnt lgkmcnt(6)
	v_pk_fma_f32 v[32:33], v[136:137], v[32:33], v[176:177] op_sel_hi:[0,1,1]
	v_pk_fma_f32 v[38:39], v[136:137], v[38:39], v[178:179] op_sel_hi:[0,1,1]
	v_pk_fma_f32 v[36:37], v[136:137], v[36:37], v[180:181] op_sel_hi:[0,1,1]
	v_pk_fma_f32 v[34:35], v[136:137], v[34:35], v[182:183] op_sel_hi:[0,1,1]
	v_pk_mul_f32 v[184:185], v[32:33], v[98:99]
	v_pk_mul_f32 v[176:177], v[112:113], v[108:109] op_sel:[0,1]
	v_pk_fma_f32 v[184:185], v[38:39], v[100:101], v[184:185]
	v_pk_mul_f32 v[178:179], v[114:115], v[108:109] op_sel:[0,1]
	v_pk_fma_f32 v[184:185], v[36:37], v[102:103], v[184:185]
	v_pk_mul_f32 v[180:181], v[116:117], v[108:109] op_sel:[0,1]
	v_pk_fma_f32 v[184:185], v[34:35], v[104:105], v[184:185]
	v_pk_mul_f32 v[182:183], v[118:119], v[108:109] op_sel:[0,1]
	v_add_f32_e32 v162, v184, v185
	ds_read_b128 v[112:115], v84 offset:5920
	ds_read_b128 v[116:119], v84 offset:6176
	ds_read_b128 v[98:101], v84 offset:5248
	ds_read_b128 v[102:105], v84 offset:5504
	s_waitcnt lgkmcnt(4)
; __device__ __forceinline__ void ssd_scan_unit(CP p, int l, int u, char* smem) {
;     ...
;   auto gload = [&](int c) {
;     const int rb = rowof(b, c * 16);
; #pragma unroll
;     for (int x = 0; x < 2; ++x) {
;       const int e = tid + x * 256, tok = e >> 5, rem = e & 31, which = rem >> 4, part = rem & 15;
;       st[x] = *reinterpret_cast<const uint4*>(SS + (size_t)(rb + tok) * 768 + 256 + which * 256 + g * 128 + part * 8);
;     }
;     {
;       const int tok = tid >> 4, pp = tid & 15;
;       stxr = SS[(size_t)(rb + tok) * 768 + h * 64 + q * 16 + pp];
;       stdt = SD[(size_t)(rb + tok) * 4 + h];
;     }
;   };
;   auto lwrite = [&](int bi) {
; #pragma unroll
;     for (int x = 0; x < 2; ++x) {
;       const int e = tid + x * 256, tok = e >> 5, rem = e & 31, which = rem >> 4, part = rem & 15;
;       float* d = buf + bi * 16 * SST + tok * SST + which * 128 + part * 8;
;       *reinterpret_cast<float4*>(d) = make_float4(lo2f(st[x].x), hi2f(st[x].x), lo2f(st[x].y), hi2f(st[x].y));
;       *reinterpret_cast<float4*>(d + 4) = make_float4(lo2f(st[x].z), hi2f(st[x].z), lo2f(st[x].w), hi2f(st[x].w));
;     }
;     {
;       const int tok = tid >> 4, pp = tid & 15;
;       float* d = buf + bi * 16 * SST + tok * SST;
;       const float stx = bf2f(stxr);
;       d[256 + pp] = stx * stdt;
;     ...
;     for (int s = 0; s < 16; ++s) {
;       const float* sb = cb + (s + 1) * SST;
;       const float4 B0n = *reinterpret_cast<const float4*>(sb + j * 4), B1n = *reinterpret_cast<const float4*>(sb + 64 + j * 4);
;       const float4 C0n = *reinterpret_cast<const float4*>(sb + 128 + j * 4), C1n = *reinterpret_cast<const float4*>(sb + 192 + j * 4);
;       const float xdtn = sb[256 + prow], xrn = sb[272 + prow], an = sb[288];
;       __builtin_amdgcn_sched_barrier(0);
;       hs[0] = fmaf(a, hs[0], xdt * B0.x); hs[1] = fmaf(a, hs[1], xdt * B0.y); hs[2] = fmaf(a, hs[2], xdt * B0.z); hs[3] = fmaf(a, hs[3], xdt * B0.w);
;       hs[4] = fmaf(a, hs[4], xdt * B1.x); hs[5] = fmaf(a, hs[5], xdt * B1.y); hs[6] = fmaf(a, hs[6], xdt * B1.z); hs[7] = fmaf(a, hs[7], xdt * B1.w);
;       float y = hs[0] * C0.x + hs[1] * C0.y + hs[2] * C0.z + hs[3] * C0.w + hs[4] * C1.x + hs[5] * C1.y + hs[6] * C1.z + hs[7] * C1.w;
;       y = allreduce16(y);
;       y = fmaf(Dh, xr, y);
;       if (j == s) ykeep = y;
;       B0 = B0n; B1 = B1n; C0 = C0n; C1 = C1n; xdt = xdtn; xr = xrn; a = an;
;     }
	v_pk_fma_f32 v[32:33], v[136:137], v[32:33], v[176:177] op_sel:[1,0,0]
	v_pk_fma_f32 v[38:39], v[136:137], v[38:39], v[178:179] op_sel:[1,0,0]
	v_pk_fma_f32 v[36:37], v[136:137], v[36:37], v[180:181] op_sel:[1,0,0]
	v_pk_fma_f32 v[34:35], v[136:137], v[34:35], v[182:183] op_sel:[1,0,0]
	v_pk_mul_f32 v[184:185], v[32:33], v[120:121]
	v_pk_mul_f32 v[176:177], v[90:91], v[128:129] op_sel_hi:[1,0]
	v_pk_fma_f32 v[184:185], v[38:39], v[122:123], v[184:185]
	v_pk_mul_f32 v[178:179], v[92:93], v[128:129] op_sel_hi:[1,0]
	v_pk_fma_f32 v[184:185], v[36:37], v[124:125], v[184:185]
	v_pk_mul_f32 v[180:181], v[94:95], v[128:129] op_sel_hi:[1,0]
	v_pk_fma_f32 v[184:185], v[34:35], v[126:127], v[184:185]
	v_pk_mul_f32 v[182:183], v[96:97], v[128:129] op_sel_hi:[1,0]
	v_add_f32_e32 v163, v184, v185
	ds_read_b128 v[90:93], v84 offset:7104
	ds_read_b128 v[94:97], v84 offset:7360
	ds_read_b128 v[120:123], v84 offset:6432
	ds_read_b128 v[124:127], v84 offset:6688
	s_waitcnt lgkmcnt(4)
	v_pk_fma_f32 v[32:33], v[138:139], v[32:33], v[176:177] op_sel_hi:[0,1,1]
	v_pk_fma_f32 v[38:39], v[138:139], v[38:39], v[178:179] op_sel_hi:[0,1,1]
	v_pk_fma_f32 v[36:37], v[138:139], v[36:37], v[180:181] op_sel_hi:[0,1,1]
	v_pk_fma_f32 v[34:35], v[138:139], v[34:35], v[182:183] op_sel_hi:[0,1,1]
	v_pk_mul_f32 v[184:185], v[32:33], v[98:99]
	v_pk_mul_f32 v[176:177], v[112:113], v[128:129] op_sel:[0,1]
	v_pk_fma_f32 v[184:185], v[38:39], v[100:101], v[184:185]
	v_pk_mul_f32 v[178:179], v[114:115], v[128:129] op_sel:[0,1]
	v_pk_fma_f32 v[184:185], v[36:37], v[102:103], v[184:185]
	v_pk_mul_f32 v[180:181], v[116:117], v[128:129] op_sel:[0,1]
	v_pk_fma_f32 v[184:185], v[34:35], v[104:105], v[184:185]
	v_pk_mul_f32 v[182:183], v[118:119], v[128:129] op_sel:[0,1]
	v_add_f32_e32 v164, v184, v185
	ds_read_b128 v[112:115], v84 offset:8288
	ds_read_b128 v[116:119], v84 offset:8544
	ds_read_b128 v[98:101], v84 offset:7616
	ds_read_b128 v[102:105], v84 offset:7872
	ds_read_b128 v[106:109], v85 offset:1056
	ds_read_b128 v[134:137], v86 offset:37920
	s_waitcnt lgkmcnt(6)
	v_pk_fma_f32 v[32:33], v[138:139], v[32:33], v[176:177] op_sel:[1,0,0]
	v_pk_fma_f32 v[38:39], v[138:139], v[38:39], v[178:179] op_sel:[1,0,0]
	v_pk_fma_f32 v[36:37], v[138:139], v[36:37], v[180:181] op_sel:[1,0,0]
	v_pk_fma_f32 v[34:35], v[138:139], v[34:35], v[182:183] op_sel:[1,0,0]
	v_pk_mul_f32 v[184:185], v[32:33], v[120:121]
	v_pk_mul_f32 v[176:177], v[90:91], v[130:131] op_sel_hi:[1,0]
	v_pk_fma_f32 v[184:185], v[38:39], v[122:123], v[184:185]
	v_pk_mul_f32 v[178:179], v[92:93], v[130:131] op_sel_hi:[1,0]
	v_pk_fma_f32 v[184:185], v[36:37], v[124:125], v[184:185]
	v_pk_mul_f32 v[180:181], v[94:95], v[130:131] op_sel_hi:[1,0]
	v_pk_fma_f32 v[184:185], v[34:35], v[126:127], v[184:185]
	v_pk_mul_f32 v[182:183], v[96:97], v[130:131] op_sel_hi:[1,0]
	v_add_f32_e32 v165, v184, v185
	ds_read_b128 v[90:93], v84 offset:9472
	ds_read_b128 v[94:97], v84 offset:9728
	ds_read_b128 v[120:123], v84 offset:8800
	ds_read_b128 v[124:127], v84 offset:9056
	s_waitcnt lgkmcnt(6)
	v_pk_fma_f32 v[32:33], v[140:141], v[32:33], v[176:177] op_sel_hi:[0,1,1]
	v_pk_fma_f32 v[38:39], v[140:141], v[38:39], v[178:179] op_sel_hi:[0,1,1]
	v_pk_fma_f32 v[36:37], v[140:141], v[36:37], v[180:181] op_sel_hi:[0,1,1]
	v_pk_fma_f32 v[34:35], v[140:141], v[34:35], v[182:183] op_sel_hi:[0,1,1]
	v_pk_mul_f32 v[184:185], v[32:33], v[98:99]
	v_pk_mul_f32 v[176:177], v[112:113], v[130:131] op_sel:[0,1]
	v_pk_fma_f32 v[184:185], v[38:39], v[100:101], v[184:185]
	v_pk_mul_f32 v[178:179], v[114:115], v[130:131] op_sel:[0,1]
	v_pk_fma_f32 v[184:185], v[36:37], v[102:103], v[184:185]
	v_pk_mul_f32 v[180:181], v[116:117], v[130:131] op_sel:[0,1]
	v_pk_fma_f32 v[184:185], v[34:35], v[104:105], v[184:185]
	v_pk_mul_f32 v[182:183], v[118:119], v[130:131] op_sel:[0,1]
	v_add_f32_e32 v166, v184, v185
	ds_read_b128 v[112:115], v84 offset:10656
	ds_read_b128 v[116:119], v84 offset:10912
	ds_read_b128 v[98:101], v84 offset:9984
	ds_read_b128 v[102:105], v84 offset:10240
	s_waitcnt lgkmcnt(4)
	v_pk_fma_f32 v[32:33], v[140:141], v[32:33], v[176:177] op_sel:[1,0,0]
	v_pk_fma_f32 v[38:39], v[140:141], v[38:39], v[178:179] op_sel:[1,0,0]
	v_pk_fma_f32 v[36:37], v[140:141], v[36:37], v[180:181] op_sel:[1,0,0]
	v_pk_fma_f32 v[34:35], v[140:141], v[34:35], v[182:183] op_sel:[1,0,0]
	v_pk_mul_f32 v[184:185], v[32:33], v[120:121]
	v_pk_mul_f32 v[176:177], v[90:91], v[106:107] op_sel_hi:[1,0]
	v_pk_fma_f32 v[184:185], v[38:39], v[122:123], v[184:185]
	v_pk_mul_f32 v[178:179], v[92:93], v[106:107] op_sel_hi:[1,0]
	v_pk_fma_f32 v[184:185], v[36:37], v[124:125], v[184:185]
	v_pk_mul_f32 v[180:181], v[94:95], v[106:107] op_sel_hi:[1,0]
	v_pk_fma_f32 v[184:185], v[34:35], v[126:127], v[184:185]
	v_pk_mul_f32 v[182:183], v[96:97], v[106:107] op_sel_hi:[1,0]
	v_add_f32_e32 v167, v184, v185
	ds_read_b128 v[90:93], v84 offset:11840
	ds_read_b128 v[94:97], v84 offset:12096
	ds_read_b128 v[120:123], v84 offset:11168
	ds_read_b128 v[124:127], v84 offset:11424
	s_waitcnt vmcnt(0)
	s_bitcmp1_b32 s28, 0
	s_cselect_b32 s2, 0x4a00, 0
	s_cselect_b32 s5, 0x40, 0
	s_add_i32 s2, s63, s2
	v_lshl_add_u32 v8, v50, 2, s2
	v_add3_u32 v18, v8, v51, v52
	v_lshlrev_b32_e32 v12, 16, v0
	v_and_b32_e32 v13, 0xffff0000, v0
	v_lshlrev_b32_e32 v14, 16, v1
	v_and_b32_e32 v15, 0xffff0000, v1
	ds_write_b128 v18, v[12:15]
	v_lshlrev_b32_e32 v12, 16, v2
	v_and_b32_e32 v13, 0xffff0000, v2
	v_lshlrev_b32_e32 v14, 16, v3
	v_and_b32_e32 v15, 0xffff0000, v3
	ds_write_b128 v18, v[12:15] offset:16
	v_lshl_add_u32 v8, v53, 2, s2
	v_add3_u32 v18, v8, v51, v52
	v_lshlrev_b32_e32 v12, 16, v4
	v_and_b32_e32 v13, 0xffff0000, v4
	v_lshlrev_b32_e32 v14, 16, v5
	v_and_b32_e32 v15, 0xffff0000, v5
	ds_write_b128 v18, v[12:15]
	v_lshlrev_b32_e32 v12, 16, v6
	v_and_b32_e32 v13, 0xffff0000, v6
	v_lshlrev_b32_e32 v14, 16, v7
	v_and_b32_e32 v15, 0xffff0000, v7
	ds_write_b128 v18, v[12:15] offset:16
	v_lshlrev_b32_e32 v9, 16, v49
	v_mul_f32_e32 v10, v54, v9
	v_add_u32_e32 v11, s2, v83
	ds_write2_b32 v11, v10, v9 offset1:16
	v_mul_f32_e32 v9, v54, v46
	v_mul_f32_e32 v9, 0xbfb8aa3b, v9
	v_exp_f32_e32 v9, v9
	v_lshl_add_u32 v8, v45, 2, s63
	v_add_u32_e32 v8, s5, v8
	ds_write_b32 v8, v9 offset:37888
	s_cmpk_gt_i32 s4, 0x7e
	s_cbranch_scc1 .Lsd_skipgl
	s_add_i32 s5, s4, 2
	s_lshl_b32 s5, s5, 4
	s_add_i32 s5, s5, s11
	v_add_u32_e32 v8, s5, v45
	v_add_u32_e32 v0, s5, v47
	v_add_u32_e32 v4, s5, v48
	v_ashrrev_i32_e32 v9, 31, v8
	v_mad_i64_i32 v[0:1], s[12:13], v0, s0, v[30:31]
	v_mad_i64_i32 v[4:5], s[12:13], v4, s0, v[30:31]
	v_mad_i64_i32 v[10:11], s[12:13], v8, s0, v[26:27]
	v_lshl_add_u64 v[8:9], v[8:9], 4, s[40:41]
	global_load_dwordx4 v[0:3], v[0:1], off offset:512
	global_load_dwordx4 v[4:7], v[4:5], off offset:512
	global_load_ushort v49, v[10:11], off
	global_load_dword v54, v[8:9], off
; __device__ __forceinline__ void ssd_scan_unit(CP p, int l, int u, char* smem) {
;     ...
;     for (int s = 0; s < 16; ++s) {
;       const float* sb = cb + (s + 1) * SST;
;       const float4 B0n = *reinterpret_cast<const float4*>(sb + j * 4), B1n = *reinterpret_cast<const float4*>(sb + 64 + j * 4);
;       const float4 C0n = *reinterpret_cast<const float4*>(sb + 128 + j * 4), C1n = *reinterpret_cast<const float4*>(sb + 192 + j * 4);
;       const float xdtn = sb[256 + prow], xrn = sb[272 + prow], an = sb[288];
;       __builtin_amdgcn_sched_barrier(0);
;       hs[0] = fmaf(a, hs[0], xdt * B0.x); hs[1] = fmaf(a, hs[1], xdt * B0.y); hs[2] = fmaf(a, hs[2], xdt * B0.z); hs[3] = fmaf(a, hs[3], xdt * B0.w);
;       hs[4] = fmaf(a, hs[4], xdt * B1.x); hs[5] = fmaf(a, hs[5], xdt * B1.y); hs[6] = fmaf(a, hs[6], xdt * B1.z); hs[7] = fmaf(a, hs[7], xdt * B1.w);
;       float y = hs[0] * C0.x + hs[1] * C0.y + hs[2] * C0.z + hs[3] * C0.w + hs[4] * C1.x + hs[5] * C1.y + hs[6] * C1.z + hs[7] * C1.w;
;       y = allreduce16(y);
;       y = fmaf(Dh, xr, y);
;       if (j == s) ykeep = y;
;       B0 = B0n; B1 = B1n; C0 = C0n; C1 = C1n; xdt = xdtn; xr = xrn; a = an;
;     }
.Lsd_skipgl:
	s_waitcnt lgkmcnt(10)
	v_pk_fma_f32 v[32:33], v[134:135], v[32:33], v[176:177] op_sel_hi:[0,1,1]
	v_pk_fma_f32 v[38:39], v[134:135], v[38:39], v[178:179] op_sel_hi:[0,1,1]
	v_pk_fma_f32 v[36:37], v[134:135], v[36:37], v[180:181] op_sel_hi:[0,1,1]
	v_pk_fma_f32 v[34:35], v[134:135], v[34:35], v[182:183] op_sel_hi:[0,1,1]
	v_pk_mul_f32 v[184:185], v[32:33], v[98:99]
	v_pk_mul_f32 v[176:177], v[112:113], v[106:107] op_sel:[0,1]
	v_pk_fma_f32 v[184:185], v[38:39], v[100:101], v[184:185]
	v_pk_mul_f32 v[178:179], v[114:115], v[106:107] op_sel:[0,1]
	v_pk_fma_f32 v[184:185], v[36:37], v[102:103], v[184:185]
	v_pk_mul_f32 v[180:181], v[116:117], v[106:107] op_sel:[0,1]
	v_pk_fma_f32 v[184:185], v[34:35], v[104:105], v[184:185]
	v_pk_mul_f32 v[182:183], v[118:119], v[106:107] op_sel:[0,1]
	v_add_f32_e32 v168, v184, v185
	ds_read_b128 v[112:115], v84 offset:13024
	ds_read_b128 v[116:119], v84 offset:13280
	ds_read_b128 v[98:101], v84 offset:12352
	ds_read_b128 v[102:105], v84 offset:12608
	ds_read_b128 v[128:131], v85 offset:1072
	ds_read_b128 v[138:141], v86 offset:37936
	s_waitcnt lgkmcnt(12)
	v_pk_fma_f32 v[32:33], v[134:135], v[32:33], v[176:177] op_sel:[1,0,0]
	v_pk_fma_f32 v[38:39], v[134:135], v[38:39], v[178:179] op_sel:[1,0,0]
	v_pk_fma_f32 v[36:37], v[134:135], v[36:37], v[180:181] op_sel:[1,0,0]
	v_pk_fma_f32 v[34:35], v[134:135], v[34:35], v[182:183] op_sel:[1,0,0]
	v_pk_mul_f32 v[184:185], v[32:33], v[120:121]
	v_pk_mul_f32 v[176:177], v[90:91], v[108:109] op_sel_hi:[1,0]
	v_pk_fma_f32 v[184:185], v[38:39], v[122:123], v[184:185]
	v_pk_mul_f32 v[178:179], v[92:93], v[108:109] op_sel_hi:[1,0]
	v_pk_fma_f32 v[184:185], v[36:37], v[124:125], v[184:185]
	v_pk_mul_f32 v[180:181], v[94:95], v[108:109] op_sel_hi:[1,0]
	v_pk_fma_f32 v[184:185], v[34:35], v[126:127], v[184:185]
	v_pk_mul_f32 v[182:183], v[96:97], v[108:109] op_sel_hi:[1,0]
	v_add_f32_e32 v169, v184, v185
	ds_read_b128 v[90:93], v84 offset:14208
	ds_read_b128 v[94:97], v84 offset:14464
	ds_read_b128 v[120:123], v84 offset:13536
	ds_read_b128 v[124:127], v84 offset:13792
	s_waitcnt lgkmcnt(6)
	v_pk_fma_f32 v[32:33], v[136:137], v[32:33], v[176:177] op_sel_hi:[0,1,1]
	v_pk_fma_f32 v[38:39], v[136:137], v[38:39], v[178:179] op_sel_hi:[0,1,1]
	v_pk_fma_f32 v[36:37], v[136:137], v[36:37], v[180:181] op_sel_hi:[0,1,1]
	v_pk_fma_f32 v[34:35], v[136:137], v[34:35], v[182:183] op_sel_hi:[0,1,1]
	v_pk_mul_f32 v[184:185], v[32:33], v[98:99]
	v_pk_mul_f32 v[176:177], v[112:113], v[108:109] op_sel:[0,1]
	v_pk_fma_f32 v[184:185], v[38:39], v[100:101], v[184:185]
	v_pk_mul_f32 v[178:179], v[114:115], v[108:109] op_sel:[0,1]
	v_pk_fma_f32 v[184:185], v[36:37], v[102:103], v[184:185]
	v_pk_mul_f32 v[180:181], v[116:117], v[108:109] op_sel:[0,1]
	v_pk_fma_f32 v[184:185], v[34:35], v[104:105], v[184:185]
	v_pk_mul_f32 v[182:183], v[118:119], v[108:109] op_sel:[0,1]
	v_add_f32_e32 v170, v184, v185
	ds_read_b128 v[112:115], v84 offset:15392
	ds_read_b128 v[116:119], v84 offset:15648
	ds_read_b128 v[98:101], v84 offset:14720
	ds_read_b128 v[102:105], v84 offset:14976
	s_waitcnt lgkmcnt(4)
	v_pk_fma_f32 v[32:33], v[136:137], v[32:33], v[176:177] op_sel:[1,0,0]
	v_pk_fma_f32 v[38:39], v[136:137], v[38:39], v[178:179] op_sel:[1,0,0]
	v_pk_fma_f32 v[36:37], v[136:137], v[36:37], v[180:181] op_sel:[1,0,0]
	v_pk_fma_f32 v[34:35], v[136:137], v[34:35], v[182:183] op_sel:[1,0,0]
	v_pk_mul_f32 v[184:185], v[32:33], v[120:121]
	v_pk_mul_f32 v[176:177], v[90:91], v[128:129] op_sel_hi:[1,0]
	v_pk_fma_f32 v[184:185], v[38:39], v[122:123], v[184:185]
	v_pk_mul_f32 v[178:179], v[92:93], v[128:129] op_sel_hi:[1,0]
	v_pk_fma_f32 v[184:185], v[36:37], v[124:125], v[184:185]
	v_pk_mul_f32 v[180:181], v[94:95], v[128:129] op_sel_hi:[1,0]
	v_pk_fma_f32 v[184:185], v[34:35], v[126:127], v[184:185]
	v_pk_mul_f32 v[182:183], v[96:97], v[128:129] op_sel_hi:[1,0]
	v_add_f32_e32 v171, v184, v185
	ds_read_b128 v[90:93], v84 offset:16576
	ds_read_b128 v[94:97], v84 offset:16832
	ds_read_b128 v[120:123], v84 offset:15904
	ds_read_b128 v[124:127], v84 offset:16160
	s_waitcnt lgkmcnt(4)
	v_pk_fma_f32 v[32:33], v[138:139], v[32:33], v[176:177] op_sel_hi:[0,1,1]
	v_pk_fma_f32 v[38:39], v[138:139], v[38:39], v[178:179] op_sel_hi:[0,1,1]
	v_pk_fma_f32 v[36:37], v[138:139], v[36:37], v[180:181] op_sel_hi:[0,1,1]
	v_pk_fma_f32 v[34:35], v[138:139], v[34:35], v[182:183] op_sel_hi:[0,1,1]
	v_pk_mul_f32 v[184:185], v[32:33], v[98:99]
	v_pk_mul_f32 v[176:177], v[112:113], v[128:129] op_sel:[0,1]
	v_pk_fma_f32 v[184:185], v[38:39], v[100:101], v[184:185]
	v_pk_mul_f32 v[178:179], v[114:115], v[128:129] op_sel:[0,1]
	v_pk_fma_f32 v[184:185], v[36:37], v[102:103], v[184:185]
	v_pk_mul_f32 v[180:181], v[116:117], v[128:129] op_sel:[0,1]
	v_pk_fma_f32 v[184:185], v[34:35], v[104:105], v[184:185]
	v_pk_mul_f32 v[182:183], v[118:119], v[128:129] op_sel:[0,1]
	v_add_f32_e32 v172, v184, v185
	ds_read_b128 v[112:115], v84 offset:17760
	ds_read_b128 v[116:119], v84 offset:18016
	ds_read_b128 v[98:101], v84 offset:17088
	ds_read_b128 v[102:105], v84 offset:17344
	s_waitcnt lgkmcnt(4)
; __device__ __forceinline__ bf16_t f2bf(float f) { return (bf16_t)(pack2(f, 0.f) & 0xffffu); }
; __device__ __forceinline__ int tidx() { int t = threadIdx.x & 255; asm volatile("" : "+v"(t)); return t; }
; __device__ __forceinline__ int half_id() { int t = (int)(threadIdx.x >> 8); asm volatile("" : "+v"(t)); return __builtin_amdgcn_readfirstlane(t); }
; #define LAS3 __attribute__((address_space(3)))
; __device__ __forceinline__ void half_barrier(char* smem_half) {
;   const int h = half_id();
;   LAS3 unsigned* cnt = (LAS3 unsigned*)(smem_half + (2 - h) * 65536 + 8 + h * 4);
;   asm volatile("s_waitcnt lgkmcnt(0)" ::: "memory");
;   if ((tidx() & 63) == 0) {
;     const unsigned old = __hip_atomic_fetch_add(cnt, 1u, __ATOMIC_RELAXED, __HIP_MEMORY_SCOPE_WORKGROUP);
;     const unsigned target = (old & ~3u) + 4u;
;     while (__hip_atomic_load(cnt, __ATOMIC_RELAXED, __HIP_MEMORY_SCOPE_WORKGROUP) < target) __builtin_amdgcn_s_sleep(1);
;   }
; __device__ __forceinline__ void ssd_scan_unit(CP p, int l, int u, char* smem) {
;     ...
;       float y = hs[0] * C0.x + hs[1] * C0.y + hs[2] * C0.z + hs[3] * C0.w + hs[4] * C1.x + hs[5] * C1.y + hs[6] * C1.z + hs[7] * C1.w;
;       y = allreduce16(y);
;       y = fmaf(Dh, xr, y);
;       if (j == s) ykeep = y;
;       B0 = B0n; B1 = B1n; C0 = C0n; C1 = C1n; xdt = xdtn; xr = xrn; a = an;
;     }
;     Y[(size_t)(rowof(b, c * 16) + j) * 1024 + h * 64 + q * 16 + prow] = f2bf(ykeep);
;     if (c + 1 < NCH) lwrite((c + 1) & 1);
;     half_barrier(smem);
	v_pk_fma_f32 v[32:33], v[138:139], v[32:33], v[176:177] op_sel:[1,0,0]
	v_pk_fma_f32 v[38:39], v[138:139], v[38:39], v[178:179] op_sel:[1,0,0]
	v_pk_fma_f32 v[36:37], v[138:139], v[36:37], v[180:181] op_sel:[1,0,0]
	v_pk_fma_f32 v[34:35], v[138:139], v[34:35], v[182:183] op_sel:[1,0,0]
	v_pk_mul_f32 v[184:185], v[32:33], v[120:121]
	v_pk_mul_f32 v[176:177], v[90:91], v[130:131] op_sel_hi:[1,0]
	v_pk_fma_f32 v[184:185], v[38:39], v[122:123], v[184:185]
	v_pk_mul_f32 v[178:179], v[92:93], v[130:131] op_sel_hi:[1,0]
	v_pk_fma_f32 v[184:185], v[36:37], v[124:125], v[184:185]
	v_pk_mul_f32 v[180:181], v[94:95], v[130:131] op_sel_hi:[1,0]
	v_pk_fma_f32 v[184:185], v[34:35], v[126:127], v[184:185]
	v_pk_mul_f32 v[182:183], v[96:97], v[130:131] op_sel_hi:[1,0]
	v_add_f32_e32 v173, v184, v185
	ds_read_b128 v[120:123], v84 offset:18272
	ds_read_b128 v[124:127], v84 offset:18528
	s_waitcnt lgkmcnt(2)
	v_pk_fma_f32 v[32:33], v[140:141], v[32:33], v[176:177] op_sel_hi:[0,1,1]
	v_pk_fma_f32 v[38:39], v[140:141], v[38:39], v[178:179] op_sel_hi:[0,1,1]
	v_pk_fma_f32 v[36:37], v[140:141], v[36:37], v[180:181] op_sel_hi:[0,1,1]
	v_pk_fma_f32 v[34:35], v[140:141], v[34:35], v[182:183] op_sel_hi:[0,1,1]
	v_pk_mul_f32 v[184:185], v[32:33], v[98:99]
	v_pk_mul_f32 v[176:177], v[112:113], v[130:131] op_sel:[0,1]
	v_pk_fma_f32 v[184:185], v[38:39], v[100:101], v[184:185]
	v_pk_mul_f32 v[178:179], v[114:115], v[130:131] op_sel:[0,1]
	v_pk_fma_f32 v[184:185], v[36:37], v[102:103], v[184:185]
	v_pk_mul_f32 v[180:181], v[116:117], v[130:131] op_sel:[0,1]
	v_pk_fma_f32 v[184:185], v[34:35], v[104:105], v[184:185]
	v_pk_mul_f32 v[182:183], v[118:119], v[130:131] op_sel:[0,1]
	v_add_f32_e32 v174, v184, v185
	s_waitcnt lgkmcnt(0)
	v_pk_fma_f32 v[32:33], v[140:141], v[32:33], v[176:177] op_sel:[1,0,0]
	v_pk_fma_f32 v[38:39], v[140:141], v[38:39], v[178:179] op_sel:[1,0,0]
	v_pk_fma_f32 v[36:37], v[140:141], v[36:37], v[180:181] op_sel:[1,0,0]
	v_pk_fma_f32 v[34:35], v[140:141], v[34:35], v[182:183] op_sel:[1,0,0]
	v_pk_mul_f32 v[184:185], v[32:33], v[120:121]
	v_pk_fma_f32 v[184:185], v[38:39], v[122:123], v[184:185]
	v_pk_fma_f32 v[184:185], v[36:37], v[124:125], v[184:185]
	v_pk_fma_f32 v[184:185], v[34:35], v[126:127], v[184:185]
	v_add_f32_e32 v175, v184, v185
	v_add_f32_dpp v160, v160, v160 row_ror:8 row_mask:0xf bank_mask:0x3 bound_ctrl:1
	v_add_f32_dpp v161, v161, v161 row_ror:8 row_mask:0xf bank_mask:0x3 bound_ctrl:1
	v_add_f32_dpp v162, v162, v162 row_ror:8 row_mask:0xf bank_mask:0x3 bound_ctrl:1
	v_add_f32_dpp v163, v163, v163 row_ror:8 row_mask:0xf bank_mask:0x3 bound_ctrl:1
	v_add_f32_dpp v164, v164, v164 row_ror:8 row_mask:0xf bank_mask:0x3 bound_ctrl:1
	v_add_f32_dpp v165, v165, v165 row_ror:8 row_mask:0xf bank_mask:0x3 bound_ctrl:1
	v_add_f32_dpp v166, v166, v166 row_ror:8 row_mask:0xf bank_mask:0x3 bound_ctrl:1
	v_add_f32_dpp v167, v167, v167 row_ror:8 row_mask:0xf bank_mask:0x3 bound_ctrl:1
	v_add_f32_dpp v160, v168, v168 row_ror:8 row_mask:0xf bank_mask:0xc bound_ctrl:1
	v_add_f32_dpp v161, v169, v169 row_ror:8 row_mask:0xf bank_mask:0xc bound_ctrl:1
	v_add_f32_dpp v162, v170, v170 row_ror:8 row_mask:0xf bank_mask:0xc bound_ctrl:1
	v_add_f32_dpp v163, v171, v171 row_ror:8 row_mask:0xf bank_mask:0xc bound_ctrl:1
	v_add_f32_dpp v164, v172, v172 row_ror:8 row_mask:0xf bank_mask:0xc bound_ctrl:1
	v_add_f32_dpp v165, v173, v173 row_ror:8 row_mask:0xf bank_mask:0xc bound_ctrl:1
	v_add_f32_dpp v166, v174, v174 row_ror:8 row_mask:0xf bank_mask:0xc bound_ctrl:1
	v_add_f32_dpp v167, v175, v175 row_ror:8 row_mask:0xf bank_mask:0xc bound_ctrl:1
	v_add_f32_dpp v160, v160, v160 row_half_mirror row_mask:0xf bank_mask:0x5 bound_ctrl:1
	v_add_f32_dpp v161, v161, v161 row_half_mirror row_mask:0xf bank_mask:0x5 bound_ctrl:1
	v_add_f32_dpp v162, v162, v162 row_half_mirror row_mask:0xf bank_mask:0x5 bound_ctrl:1
	v_add_f32_dpp v163, v163, v163 row_half_mirror row_mask:0xf bank_mask:0x5 bound_ctrl:1
	v_add_f32_dpp v160, v164, v164 row_half_mirror row_mask:0xf bank_mask:0xa bound_ctrl:1
	v_add_f32_dpp v161, v165, v165 row_half_mirror row_mask:0xf bank_mask:0xa bound_ctrl:1
	v_add_f32_dpp v162, v166, v166 row_half_mirror row_mask:0xf bank_mask:0xa bound_ctrl:1
	v_add_f32_dpp v163, v167, v167 row_half_mirror row_mask:0xf bank_mask:0xa bound_ctrl:1
	v_and_b32_e32 v188, 2, v44
	v_cmp_ne_u32_e32 vcc, 0, v188
	v_and_b32_e32 v188, 1, v44
	s_nop 0
	v_cndmask_b32_e32 v189, v160, v162, vcc
	v_cndmask_b32_e32 v190, v162, v160, vcc
	v_cndmask_b32_e32 v191, v161, v163, vcc
	v_cndmask_b32_e32 v192, v163, v161, vcc
	v_cmp_ne_u32_e32 vcc, 0, v188
	v_add_f32_dpp v160, v190, v189 quad_perm:[2,3,0,1] row_mask:0xf bank_mask:0xf bound_ctrl:1
	v_add_f32_dpp v161, v192, v191 quad_perm:[2,3,0,1] row_mask:0xf bank_mask:0xf bound_ctrl:1
	v_cndmask_b32_e32 v189, v160, v161, vcc
	v_cndmask_b32_e32 v190, v161, v160, vcc
	s_nop 1
	v_add_f32_dpp v187, v190, v189 quad_perm:[1,0,3,2] row_mask:0xf bank_mask:0xf bound_ctrl:1
	v_fma_f32 v60, v43, v186, v187
	s_lshl_b32 s5, s4, 4
	s_add_i32 s5, s5, s11
	s_cmp_eq_u32 s4, 0
	s_cselect_b32 s5, s10, s5
	v_or_b32_e32 v8, s5, v44
	v_ashrrev_i32_e32 v9, 31, v8
	v_lshlrev_b64 v[8:9], 11, v[8:9]
	v_cvt_pk_bf16_f32 v10, v60, s0
	v_lshl_add_u64 v[8:9], v[28:29], 0, v[8:9]
	global_store_short v[8:9], v10, off
	s_waitcnt lgkmcnt(0)
	s_mov_b64 s[12:13], exec
	s_mov_b64 exec, 1
	ds_add_u32 v193, v195 offset:8
	s_mov_b64 exec, s[12:13]
	v_add_u32_e32 v194, 4, v194

; __device__ __forceinline__ int tidx() { int t = threadIdx.x & 255; asm volatile("" : "+v"(t)); return t; }
; __device__ __forceinline__ int half_id() { int t = (int)(threadIdx.x >> 8); asm volatile("" : "+v"(t)); return __builtin_amdgcn_readfirstlane(t); }
; #define LAS3 __attribute__((address_space(3)))
; __device__ __forceinline__ void half_barrier(char* smem_half) {
;   const int h = half_id();
;   LAS3 unsigned* cnt = (LAS3 unsigned*)(smem_half + (2 - h) * 65536 + 8 + h * 4);
;   asm volatile("s_waitcnt lgkmcnt(0)" ::: "memory");
;   if ((tidx() & 63) == 0) {
;     const unsigned old = __hip_atomic_fetch_add(cnt, 1u, __ATOMIC_RELAXED, __HIP_MEMORY_SCOPE_WORKGROUP);
;     const unsigned target = (old & ~3u) + 4u;
;     while (__hip_atomic_load(cnt, __ATOMIC_RELAXED, __HIP_MEMORY_SCOPE_WORKGROUP) < target) __builtin_amdgcn_s_sleep(1);
;   }
; __device__ __forceinline__ void ssd_scan_unit(CP p, int l, int u, char* smem) {
;     ...
;   for (int c = 0; c < NCH; ++c) {
.Lsd_bdone:
	s_mov_b32 s4, s28
	s_cmpk_lt_i32 s28, 0x81
	s_cbranch_scc1 .Lsd_head
	s_branch .LBB0_558
.LBB0_558:
	s_mov_b64 s[2:3], 0
	s_movk_i32 s72, 0x1a10
	s_movk_i32 s67, 0x407f
